# E-phase GEMM K-loop: LDS-DMA loads switched from 64-bit VGPR addresses to SGPR-base + 32-bit VGPR offset form
# speedup vs baseline: 1.0056x; 1.0056x over previous
; #define PG8_STAGE(bufoff, gbase, voff) do { _Pragma("unroll") for (int _i = 0; _i < 2; ++_i) \
;         __builtin_amdgcn_global_load_lds((const unsigned*)((const char*)(gbase) + (voff)[_i]), (LAS unsigned*)(lds + (bufoff) + ldsw + _i * 8192), 16, 0, 0); } while (0)
; #define PG8_LDA(dst, b, h) do { _Pragma("unroll") for (int m = 0; m < 4; ++m) _Pragma("unroll") for (int k = 0; k < 2; ++k) dst[m][k] = *(const LAS bf16x8*)(lds + PG8_SA(b, h) + aoff + m * 2048 + k * 1024); } while (0)
; #define PG8_LDB(dst, b, h) do { _Pragma("unroll") for (int n = 0; n < 2; ++n) _Pragma("unroll") for (int k = 0; k < 2; ++k) dst[n][k] = *(const LAS bf16x8*)(lds + PG8_SB(b, h) + boff + n * 2048 + k * 1024); } while (0)
; #define PG8_MMA(ai, bj, At, Bt) do { __builtin_amdgcn_s_setprio(1); _Pragma("unroll") for (int m = 0; m < 4; ++m) _Pragma("unroll") for (int n = 0; n < 2; ++n) _Pragma("unroll") for (int k = 0; k < 2; ++k) \
;         acc[ai][bj][m][n] = __builtin_amdgcn_mfma_f32_16x16x32_bf16(Bt[n][k], At[m][k], acc[ai][bj][m][n], 0, 0, 0); __builtin_amdgcn_s_setprio(0); } while (0)
; #define PG8_WAIT_V(n) asm volatile("s_waitcnt vmcnt(" #n ")" ::: "memory")
; #define PG8_WAIT_L(n) asm volatile("s_waitcnt lgkmcnt(" #n ")" ::: "memory")
; #define PG8_BAR __builtin_amdgcn_s_barrier()
; template <class Epi>
; __device__ __forceinline__ void gemm_phase(LAS unsigned char* lds, const Gemm g, const StaticOrder& S, const Epi& E) {
;     ...
;             const bool last = (t == nt - 2);
;             const char* a1 = cA + (size_t)(t + 1) * kstep;
;             const char* a2 = last ? nA : cA + (size_t)(t + 2) * kstep; const char* b2 = last ? nB : cB + (size_t)(t + 2) * kstep;
;             const char* a3 = a2 + kstep; const char* b3 = b2 + kstep;
;             PG8_LDB(B0, 0, 0); PG8_SCHED; PG8_LDA(At, 0, 0); PG8_STAGE(PG8_SA(1, 1), a1 + hstep, voffA);
;             PG8_WAIT_L(8); PG8_BAR; PG8_WAIT_L(0); PG8_MMA(0, 0, At, B0); PG8_BAR; PG8_SCHED;
;             PG8_LDB(B1, 0, 1); PG8_STAGE(PG8_SB(0, 0), b2, voffB);
;             PG8_BAR; PG8_WAIT_L(0); PG8_MMA(0, 1, At, B1); PG8_BAR;
;             PG8_LDA(At, 0, 1); PG8_STAGE(PG8_SA(0, 0), a2, voffA);
;             PG8_BAR; PG8_WAIT_L(0); PG8_MMA(1, 0, At, B0); PG8_BAR; PG8_SCHED;
;             PG8_STAGE(PG8_SB(0, 1), b2 + hstep, voffB);
;             PG8_WAIT_V(6); PG8_BAR; PG8_MMA(1, 1, At, B1); PG8_BAR;
.LBB0_170:
	s_add_u32 s6, s36, 0xfffc0080
	s_addc_u32 s7, s37, -1
	s_add_i32 s58, 0, 0x10000
	v_add_u32_e32 v144, s58, v147
	ds_read_b128 v[140:143], v144
	ds_read_b128 v[152:155], v144 offset:1024
	ds_read_b128 v[168:171], v144 offset:2048
	ds_read_b128 v[172:175], v144 offset:3072
	s_cmp_eq_u32 s93, 12
	s_cselect_b32 s43, s11, s7
	s_cselect_b32 s42, s71, s6
	s_cselect_b32 s7, s9, s92
	s_cselect_b32 s6, s90, s91
	s_add_i32 m0, s49, 0xc000
	ds_read_b128 v[176:179], v150
	ds_read_b128 v[180:183], v150 offset:1024
	ds_read_b128 v[184:187], v150 offset:2048
	ds_read_b128 v[204:207], v150 offset:3072
	ds_read_b128 v[208:211], v150 offset:4096
	ds_read_b128 v[212:215], v150 offset:5120
	ds_read_b128 v[216:219], v150 offset:6144
	ds_read_b128 v[226:229], v150 offset:7168
	global_load_lds_dwordx4 v136, s[36:37]
	s_add_i32 m0, s49, 0xe000
	s_nop 0
	global_load_lds_dwordx4 v138, s[36:37]
	s_waitcnt lgkmcnt(8)
	s_barrier
	s_waitcnt lgkmcnt(0)
	s_setprio 1
	s_waitcnt lgkmcnt(0)
	v_mfma_f32_16x16x32_bf16 v[126:129], v[140:143], v[176:179], v[126:129]
	v_mfma_f32_16x16x32_bf16 v[122:125], v[168:171], v[176:179], v[122:125]
	v_mfma_f32_16x16x32_bf16 v[110:113], v[140:143], v[184:187], v[110:113]
	v_mfma_f32_16x16x32_bf16 v[106:109], v[168:171], v[184:187], v[106:109]
	v_mfma_f32_16x16x32_bf16 v[94:97], v[140:143], v[208:211], v[94:97]
	v_mfma_f32_16x16x32_bf16 v[90:93], v[168:171], v[208:211], v[90:93]
	v_mfma_f32_16x16x32_bf16 v[78:81], v[140:143], v[216:219], v[78:81]
	v_mfma_f32_16x16x32_bf16 v[74:77], v[168:171], v[216:219], v[74:77]
	v_mfma_f32_16x16x32_bf16 v[126:129], v[152:155], v[180:183], v[126:129]
	v_mfma_f32_16x16x32_bf16 v[122:125], v[172:175], v[180:183], v[122:125]
	v_mfma_f32_16x16x32_bf16 v[110:113], v[152:155], v[204:207], v[110:113]
	v_mfma_f32_16x16x32_bf16 v[106:109], v[172:175], v[204:207], v[106:109]
	v_mfma_f32_16x16x32_bf16 v[94:97], v[152:155], v[212:215], v[94:97]
	v_mfma_f32_16x16x32_bf16 v[90:93], v[172:175], v[212:215], v[90:93]
	v_mfma_f32_16x16x32_bf16 v[78:81], v[152:155], v[226:229], v[78:81]
	v_mfma_f32_16x16x32_bf16 v[74:77], v[172:175], v[226:229], v[74:77]
	s_setprio 0
	s_barrier
	s_add_i32 s70, 0, 0x14000
	v_add_u32_e32 v144, s70, v147
	s_add_i32 s58, s58, s48
	ds_read_b128 v[230:233], v144
	ds_read_b128 v[234:237], v144 offset:1024
	ds_read_b128 v[238:241], v144 offset:2048
	ds_read_b128 v[242:245], v144 offset:3072
	s_mov_b32 m0, s58
	s_nop 0
	global_load_lds_dwordx4 v0, s[6:7]
	s_add_i32 m0, s58, 0x2000
	s_nop 0
	global_load_lds_dwordx4 v130, s[6:7]
	s_barrier
	s_waitcnt lgkmcnt(0)
	s_setprio 1
	s_waitcnt lgkmcnt(0)
	v_mfma_f32_16x16x32_bf16 v[118:121], v[230:233], v[176:179], v[118:121]
	v_mfma_f32_16x16x32_bf16 v[114:117], v[238:241], v[176:179], v[114:117]
	v_mfma_f32_16x16x32_bf16 v[102:105], v[230:233], v[184:187], v[102:105]
	v_mfma_f32_16x16x32_bf16 v[98:101], v[238:241], v[184:187], v[98:101]
	v_mfma_f32_16x16x32_bf16 v[86:89], v[230:233], v[208:211], v[86:89]
	v_mfma_f32_16x16x32_bf16 v[82:85], v[238:241], v[208:211], v[82:85]
	v_mfma_f32_16x16x32_bf16 v[70:73], v[230:233], v[216:219], v[70:73]
	v_mfma_f32_16x16x32_bf16 v[66:69], v[238:241], v[216:219], v[66:69]
	v_mfma_f32_16x16x32_bf16 v[118:121], v[234:237], v[180:183], v[118:121]
	v_mfma_f32_16x16x32_bf16 v[114:117], v[242:245], v[180:183], v[114:117]
	v_mfma_f32_16x16x32_bf16 v[102:105], v[234:237], v[204:207], v[102:105]
	v_mfma_f32_16x16x32_bf16 v[98:101], v[242:245], v[204:207], v[98:101]
	v_mfma_f32_16x16x32_bf16 v[86:89], v[234:237], v[212:215], v[86:89]
	v_mfma_f32_16x16x32_bf16 v[82:85], v[242:245], v[212:215], v[82:85]
	v_mfma_f32_16x16x32_bf16 v[70:73], v[234:237], v[226:229], v[70:73]
	v_mfma_f32_16x16x32_bf16 v[66:69], v[242:245], v[226:229], v[66:69]
	s_setprio 0
	s_mov_b32 m0, s49
	s_add_u32 vcc_lo, s42, 0x80
	s_addc_u32 vcc_hi, s43, 0
	s_barrier
	ds_read_b128 v[176:179], v150 offset:16384
	ds_read_b128 v[180:183], v150 offset:17408
	ds_read_b128 v[184:187], v150 offset:18432
	ds_read_b128 v[204:207], v150 offset:19456
	ds_read_b128 v[208:211], v150 offset:20480
	ds_read_b128 v[212:215], v150 offset:21504
	ds_read_b128 v[216:219], v150 offset:22528
	ds_read_b128 v[226:229], v150 offset:23552
	global_load_lds_dwordx4 v134, s[42:43]
	s_mov_b32 m0, s54
	s_nop 0
	global_load_lds_dwordx4 v132, s[42:43]
	s_barrier
	s_waitcnt lgkmcnt(0)
	s_setprio 1
	s_waitcnt lgkmcnt(0)
	v_mfma_f32_16x16x32_bf16 v[62:65], v[140:143], v[176:179], v[62:65]
	v_mfma_f32_16x16x32_bf16 v[58:61], v[168:171], v[176:179], v[58:61]
	v_mfma_f32_16x16x32_bf16 v[46:49], v[140:143], v[184:187], v[46:49]
	v_mfma_f32_16x16x32_bf16 v[42:45], v[168:171], v[184:187], v[42:45]
	v_mfma_f32_16x16x32_bf16 v[30:33], v[140:143], v[208:211], v[30:33]
	v_mfma_f32_16x16x32_bf16 v[26:29], v[168:171], v[208:211], v[26:29]
	v_mfma_f32_16x16x32_bf16 v[14:17], v[140:143], v[216:219], v[14:17]
	v_mfma_f32_16x16x32_bf16 v[10:13], v[168:171], v[216:219], v[10:13]
	v_mfma_f32_16x16x32_bf16 v[62:65], v[152:155], v[180:183], v[62:65]
	v_mfma_f32_16x16x32_bf16 v[58:61], v[172:175], v[180:183], v[58:61]
	v_mfma_f32_16x16x32_bf16 v[46:49], v[152:155], v[204:207], v[46:49]
	v_mfma_f32_16x16x32_bf16 v[42:45], v[172:175], v[204:207], v[42:45]
	v_mfma_f32_16x16x32_bf16 v[30:33], v[152:155], v[212:215], v[30:33]
	v_mfma_f32_16x16x32_bf16 v[26:29], v[172:175], v[212:215], v[26:29]
	v_mfma_f32_16x16x32_bf16 v[14:17], v[152:155], v[226:229], v[14:17]
	v_mfma_f32_16x16x32_bf16 v[10:13], v[172:175], v[226:229], v[10:13]
	s_setprio 0
	s_barrier
	s_add_u32 s60, s6, 0x40000
	s_addc_u32 s61, s7, 0
	s_add_i32 s58, s70, s48
	s_mov_b32 m0, s58
	s_nop 0
	global_load_lds_dwordx4 v0, s[60:61]
	s_add_i32 m0, s58, 0x2000
	s_nop 0
	global_load_lds_dwordx4 v130, s[60:61]
	s_waitcnt vmcnt(6)
	s_barrier
; #define PG8_STAGE(bufoff, gbase, voff) do { _Pragma("unroll") for (int _i = 0; _i < 2; ++_i) \
;         __builtin_amdgcn_global_load_lds((const unsigned*)((const char*)(gbase) + (voff)[_i]), (LAS unsigned*)(lds + (bufoff) + ldsw + _i * 8192), 16, 0, 0); } while (0)
; #define PG8_LDA(dst, b, h) do { _Pragma("unroll") for (int m = 0; m < 4; ++m) _Pragma("unroll") for (int k = 0; k < 2; ++k) dst[m][k] = *(const LAS bf16x8*)(lds + PG8_SA(b, h) + aoff + m * 2048 + k * 1024); } while (0)
; #define PG8_LDB(dst, b, h) do { _Pragma("unroll") for (int n = 0; n < 2; ++n) _Pragma("unroll") for (int k = 0; k < 2; ++k) dst[n][k] = *(const LAS bf16x8*)(lds + PG8_SB(b, h) + boff + n * 2048 + k * 1024); } while (0)
; #define PG8_MMA(ai, bj, At, Bt) do { __builtin_amdgcn_s_setprio(1); _Pragma("unroll") for (int m = 0; m < 4; ++m) _Pragma("unroll") for (int n = 0; n < 2; ++n) _Pragma("unroll") for (int k = 0; k < 2; ++k) \
;         acc[ai][bj][m][n] = __builtin_amdgcn_mfma_f32_16x16x32_bf16(Bt[n][k], At[m][k], acc[ai][bj][m][n], 0, 0, 0); __builtin_amdgcn_s_setprio(0); } while (0)
; #define PG8_WAIT_V(n) asm volatile("s_waitcnt vmcnt(" #n ")" ::: "memory")
; #define PG8_WAIT_L(n) asm volatile("s_waitcnt lgkmcnt(" #n ")" ::: "memory")
; #define PG8_BAR __builtin_amdgcn_s_barrier()
; #define PG8_SCHED __builtin_amdgcn_sched_barrier(0)
; template <class Epi>
; __device__ __forceinline__ void gemm_phase(LAS unsigned char* lds, const Gemm g, const StaticOrder& S, const Epi& E) {
;     ...
;             PG8_WAIT_V(6); PG8_BAR; PG8_MMA(1, 1, At, B1); PG8_BAR;
;             PG8_LDB(B0, 1, 0); PG8_SCHED; PG8_LDA(At, 1, 0); PG8_STAGE(PG8_SA(0, 1), a2 + hstep, voffA);
;             PG8_WAIT_L(8); PG8_BAR; PG8_WAIT_L(0); PG8_MMA(0, 0, At, B0); PG8_BAR; PG8_SCHED;
;             PG8_LDB(B1, 1, 1); PG8_STAGE(PG8_SB(1, 0), b3, voffB);
;             PG8_BAR; PG8_WAIT_L(0); PG8_MMA(0, 1, At, B1); PG8_BAR;
;             PG8_LDA(At, 1, 1); PG8_STAGE(PG8_SA(1, 0), a3, voffA);
;             PG8_BAR; PG8_WAIT_L(0); PG8_MMA(1, 0, At, B0); PG8_BAR; PG8_SCHED;
	s_setprio 1
	v_mfma_f32_16x16x32_bf16 v[54:57], v[230:233], v[176:179], v[54:57]
	v_mfma_f32_16x16x32_bf16 v[50:53], v[238:241], v[176:179], v[50:53]
	v_mfma_f32_16x16x32_bf16 v[38:41], v[230:233], v[184:187], v[38:41]
	v_mfma_f32_16x16x32_bf16 v[34:37], v[238:241], v[184:187], v[34:37]
	v_mfma_f32_16x16x32_bf16 v[22:25], v[230:233], v[208:211], v[22:25]
	v_mfma_f32_16x16x32_bf16 v[18:21], v[238:241], v[208:211], v[18:21]
	v_mfma_f32_16x16x32_bf16 v[6:9], v[230:233], v[216:219], v[6:9]
	v_mfma_f32_16x16x32_bf16 v[2:5], v[238:241], v[216:219], v[2:5]
	v_mfma_f32_16x16x32_bf16 v[54:57], v[234:237], v[180:183], v[54:57]
	v_mfma_f32_16x16x32_bf16 v[50:53], v[242:245], v[180:183], v[50:53]
	v_mfma_f32_16x16x32_bf16 v[38:41], v[234:237], v[204:207], v[38:41]
	v_mfma_f32_16x16x32_bf16 v[34:37], v[242:245], v[204:207], v[34:37]
	v_mfma_f32_16x16x32_bf16 v[22:25], v[234:237], v[212:215], v[22:25]
	v_mfma_f32_16x16x32_bf16 v[18:21], v[242:245], v[212:215], v[18:21]
	v_mfma_f32_16x16x32_bf16 v[6:9], v[234:237], v[226:229], v[6:9]
	v_mfma_f32_16x16x32_bf16 v[2:5], v[242:245], v[226:229], v[2:5]
	s_setprio 0
	s_add_i32 s58, 0, 0x18000
	v_add_u32_e32 v151, s58, v147
	s_barrier
	ds_read_b128 v[140:143], v151
	ds_read_b128 v[152:155], v151 offset:1024
	ds_read_b128 v[168:171], v151 offset:2048
	ds_read_b128 v[172:175], v151 offset:3072
	s_add_u32 s42, s42, 0x40000
	s_addc_u32 s43, s43, 0
	s_mov_b32 m0, s55
	ds_read_b128 v[176:179], v150 offset:32768
	ds_read_b128 v[180:183], v150 offset:33792
	ds_read_b128 v[184:187], v150 offset:34816
	ds_read_b128 v[204:207], v150 offset:35840
	ds_read_b128 v[208:211], v150 offset:36864
	ds_read_b128 v[212:215], v150 offset:37888
	ds_read_b128 v[216:219], v150 offset:38912
	ds_read_b128 v[226:229], v150 offset:39936
	global_load_lds_dwordx4 v134, s[42:43]
	s_mov_b32 m0, s83
	s_nop 0
	global_load_lds_dwordx4 v132, s[42:43]
	s_waitcnt lgkmcnt(8)
	s_barrier
	s_waitcnt lgkmcnt(0)
	s_setprio 1
	s_waitcnt lgkmcnt(0)
	v_mfma_f32_16x16x32_bf16 v[126:129], v[140:143], v[176:179], v[126:129]
	v_mfma_f32_16x16x32_bf16 v[122:125], v[168:171], v[176:179], v[122:125]
	v_mfma_f32_16x16x32_bf16 v[110:113], v[140:143], v[184:187], v[110:113]
	v_mfma_f32_16x16x32_bf16 v[106:109], v[168:171], v[184:187], v[106:109]
	v_mfma_f32_16x16x32_bf16 v[94:97], v[140:143], v[208:211], v[94:97]
	v_mfma_f32_16x16x32_bf16 v[90:93], v[168:171], v[208:211], v[90:93]
	v_mfma_f32_16x16x32_bf16 v[78:81], v[140:143], v[216:219], v[78:81]
	v_mfma_f32_16x16x32_bf16 v[74:77], v[168:171], v[216:219], v[74:77]
	v_mfma_f32_16x16x32_bf16 v[126:129], v[152:155], v[180:183], v[126:129]
	v_mfma_f32_16x16x32_bf16 v[122:125], v[172:175], v[180:183], v[122:125]
	v_mfma_f32_16x16x32_bf16 v[110:113], v[152:155], v[204:207], v[110:113]
	v_mfma_f32_16x16x32_bf16 v[106:109], v[172:175], v[204:207], v[106:109]
	v_mfma_f32_16x16x32_bf16 v[94:97], v[152:155], v[212:215], v[94:97]
	v_mfma_f32_16x16x32_bf16 v[90:93], v[172:175], v[212:215], v[90:93]
	v_mfma_f32_16x16x32_bf16 v[78:81], v[152:155], v[226:229], v[78:81]
	v_mfma_f32_16x16x32_bf16 v[74:77], v[172:175], v[226:229], v[74:77]
	s_setprio 0
	s_barrier
	s_add_i32 s42, 0, 0x1c000
	s_add_i32 s43, s58, s48
	v_add_u32_e32 v151, s42, v147
	s_add_u32 s60, s6, 0x80
	s_addc_u32 s61, s7, 0
	s_mov_b32 m0, s43
	ds_read_b128 v[230:233], v151
	ds_read_b128 v[234:237], v151 offset:1024
	ds_read_b128 v[238:241], v151 offset:2048
	ds_read_b128 v[242:245], v151 offset:3072
	global_load_lds_dwordx4 v0, s[60:61]
	s_add_i32 m0, s43, 0x2000
	s_nop 0
	global_load_lds_dwordx4 v130, s[60:61]
	s_barrier
	s_waitcnt lgkmcnt(0)
	s_setprio 1
	s_waitcnt lgkmcnt(0)
	v_mfma_f32_16x16x32_bf16 v[118:121], v[230:233], v[176:179], v[118:121]
	v_mfma_f32_16x16x32_bf16 v[114:117], v[238:241], v[176:179], v[114:117]
	v_mfma_f32_16x16x32_bf16 v[102:105], v[230:233], v[184:187], v[102:105]
	v_mfma_f32_16x16x32_bf16 v[98:101], v[238:241], v[184:187], v[98:101]
	v_mfma_f32_16x16x32_bf16 v[86:89], v[230:233], v[208:211], v[86:89]
	v_mfma_f32_16x16x32_bf16 v[82:85], v[238:241], v[208:211], v[82:85]
	v_mfma_f32_16x16x32_bf16 v[70:73], v[230:233], v[216:219], v[70:73]
	v_mfma_f32_16x16x32_bf16 v[66:69], v[238:241], v[216:219], v[66:69]
	v_mfma_f32_16x16x32_bf16 v[118:121], v[234:237], v[180:183], v[118:121]
	v_mfma_f32_16x16x32_bf16 v[114:117], v[242:245], v[180:183], v[114:117]
	v_mfma_f32_16x16x32_bf16 v[102:105], v[234:237], v[204:207], v[102:105]
	v_mfma_f32_16x16x32_bf16 v[98:101], v[242:245], v[204:207], v[98:101]
	v_mfma_f32_16x16x32_bf16 v[86:89], v[234:237], v[212:215], v[86:89]
	v_mfma_f32_16x16x32_bf16 v[82:85], v[242:245], v[212:215], v[82:85]
	v_mfma_f32_16x16x32_bf16 v[70:73], v[234:237], v[226:229], v[70:73]
	v_mfma_f32_16x16x32_bf16 v[66:69], v[242:245], v[226:229], v[66:69]
	s_setprio 0
	s_mov_b32 m0, s84
	s_barrier
	ds_read_b128 v[176:179], v150 offset:49152
	ds_read_b128 v[180:183], v150 offset:50176
	ds_read_b128 v[184:187], v150 offset:51200
	ds_read_b128 v[204:207], v150 offset:52224
	ds_read_b128 v[208:211], v150 offset:53248
	ds_read_b128 v[212:215], v150 offset:54272
	ds_read_b128 v[216:219], v150 offset:55296
	ds_read_b128 v[226:229], v150 offset:56320
	global_load_lds_dwordx4 v134, vcc
	s_mov_b32 m0, s85
	s_nop 0
	global_load_lds_dwordx4 v132, vcc
	s_barrier
; __device__ __forceinline__ unsigned pk2(float lo, float hi) { unsigned r; asm("v_cvt_pk_bf16_f32 %0, %1, %2" : "=v"(r) : "v"(lo), "v"(hi)); return r; }
; #define PG8_STAGE(bufoff, gbase, voff) do { _Pragma("unroll") for (int _i = 0; _i < 2; ++_i) \
;         __builtin_amdgcn_global_load_lds((const unsigned*)((const char*)(gbase) + (voff)[_i]), (LAS unsigned*)(lds + (bufoff) + ldsw + _i * 8192), 16, 0, 0); } while (0)
; #define PG8_WAIT_V(n) asm volatile("s_waitcnt vmcnt(" #n ")" ::: "memory")
; #define PG8_WAIT_L(n) asm volatile("s_waitcnt lgkmcnt(" #n ")" ::: "memory")
; #define PG8_BAR __builtin_amdgcn_s_barrier()
; #define PG8_SCHED __builtin_amdgcn_sched_barrier(0)
;     __device__ __forceinline__ void operator()(const f32x4 (&acc)[2][2][4][2], const Unit& u, int ui, int wr, int wc, int fr, int fq) const {
;         const int lrow0 = wr * 64 + fr, row0 = u.pm * BM + lrow0, col0 = u.pn * BM + wc * 32 + 8 * fq;
;         float rsv[2][4];
; #pragma unroll
;         for (int ai = 0; ai < 2; ++ai)
; #pragma unroll
;             for (int m = 0; m < 4; ++m) rsv[ai][m] = rstab[ui * 256 + lrow0 + ai * HALF + m * 16];
; #pragma unroll
;         for (int ai = 0; ai < 2; ++ai)
; #pragma unroll
;             for (int m = 0; m < 4; ++m) {
;                 const int row = row0 + ai * HALF + m * 16; const float rs = rsv[ai][m];
;                 bf16_t* rowp = O + (size_t)row * ldc + col0;
; #pragma unroll
;                 for (int bj = 0; bj < 2; ++bj) {
;                     f32x4 v0 = acc[ai][bj][m][0] * rs, v1 = acc[ai][bj][m][1] * rs;
;                     if (ACT == 1) {
; #pragma unroll
;                         for (int j = 0; j < 4; ++j) { const float a = fmaxf(v0[j], 0.f), b = fmaxf(v1[j], 0.f); v0[j] = a * a; v1[j] = b * b; }
;                     }
;                     u32x4 w; w.x = pk2(v0[0], v0[1]); w.y = pk2(v0[2], v0[3]); w.z = pk2(v1[0], v1[1]); w.w = pk2(v1[2], v1[3]);
;                     *(u32x4*)(rowp + bj * HALF) = w;
; template <class Epi>
; __device__ __forceinline__ void gemm_phase(LAS unsigned char* lds, const Gemm g, const StaticOrder& S, const Epi& E) {
;     ...
;             PG8_BAR; PG8_WAIT_L(0); PG8_MMA(1, 0, At, B0); PG8_BAR; PG8_SCHED;
;             PG8_STAGE(PG8_SB(1, 1), b3 + hstep, voffB);
;             PG8_WAIT_V(6); PG8_BAR; PG8_MMA(1, 1, At, B1); PG8_BAR;
;         }
	s_waitcnt lgkmcnt(0)
	s_setprio 1
	s_waitcnt lgkmcnt(0)
	v_mfma_f32_16x16x32_bf16 v[62:65], v[140:143], v[176:179], v[62:65]
	v_mfma_f32_16x16x32_bf16 v[58:61], v[168:171], v[176:179], v[58:61]
	v_mfma_f32_16x16x32_bf16 v[46:49], v[140:143], v[184:187], v[46:49]
	v_mfma_f32_16x16x32_bf16 v[42:45], v[168:171], v[184:187], v[42:45]
	v_mfma_f32_16x16x32_bf16 v[30:33], v[140:143], v[208:211], v[30:33]
	v_mfma_f32_16x16x32_bf16 v[26:29], v[168:171], v[208:211], v[26:29]
	v_mfma_f32_16x16x32_bf16 v[14:17], v[140:143], v[216:219], v[14:17]
	v_mfma_f32_16x16x32_bf16 v[10:13], v[168:171], v[216:219], v[10:13]
	v_mfma_f32_16x16x32_bf16 v[62:65], v[152:155], v[180:183], v[62:65]
	v_mfma_f32_16x16x32_bf16 v[58:61], v[172:175], v[180:183], v[58:61]
	v_mfma_f32_16x16x32_bf16 v[46:49], v[152:155], v[204:207], v[46:49]
	v_mfma_f32_16x16x32_bf16 v[42:45], v[172:175], v[204:207], v[42:45]
	v_mfma_f32_16x16x32_bf16 v[30:33], v[152:155], v[212:215], v[30:33]
	v_mfma_f32_16x16x32_bf16 v[26:29], v[172:175], v[212:215], v[26:29]
	v_mfma_f32_16x16x32_bf16 v[14:17], v[152:155], v[226:229], v[14:17]
	v_mfma_f32_16x16x32_bf16 v[10:13], v[172:175], v[226:229], v[10:13]
	s_setprio 0
	s_barrier
	s_add_u32 s6, s6, 0x40080
	s_addc_u32 s7, s7, 0
	s_add_i32 s42, s42, s48
	s_mov_b32 m0, s42
	s_nop 0
	global_load_lds_dwordx4 v0, s[6:7]
	s_add_i32 m0, s42, 0x2000
	s_nop 0
	global_load_lds_dwordx4 v130, s[6:7]
	s_waitcnt vmcnt(6)
	s_barrier
	s_setprio 1
	v_mfma_f32_16x16x32_bf16 v[54:57], v[230:233], v[176:179], v[54:57]
	v_mfma_f32_16x16x32_bf16 v[50:53], v[238:241], v[176:179], v[50:53]
	v_mfma_f32_16x16x32_bf16 v[38:41], v[230:233], v[184:187], v[38:41]
	v_mfma_f32_16x16x32_bf16 v[34:37], v[238:241], v[184:187], v[34:37]
	v_mfma_f32_16x16x32_bf16 v[22:25], v[230:233], v[208:211], v[22:25]
	v_mfma_f32_16x16x32_bf16 v[18:21], v[238:241], v[208:211], v[18:21]
	v_mfma_f32_16x16x32_bf16 v[6:9], v[230:233], v[216:219], v[6:9]
	v_mfma_f32_16x16x32_bf16 v[2:5], v[238:241], v[216:219], v[2:5]
	v_mfma_f32_16x16x32_bf16 v[54:57], v[234:237], v[180:183], v[54:57]
	v_mfma_f32_16x16x32_bf16 v[50:53], v[242:245], v[180:183], v[50:53]
	v_mfma_f32_16x16x32_bf16 v[38:41], v[234:237], v[204:207], v[38:41]
	v_mfma_f32_16x16x32_bf16 v[34:37], v[242:245], v[204:207], v[34:37]
	v_mfma_f32_16x16x32_bf16 v[22:25], v[234:237], v[212:215], v[22:25]
	v_mfma_f32_16x16x32_bf16 v[18:21], v[242:245], v[212:215], v[18:21]
	v_mfma_f32_16x16x32_bf16 v[6:9], v[234:237], v[226:229], v[6:9]
	v_mfma_f32_16x16x32_bf16 v[2:5], v[242:245], v[226:229], v[2:5]
	s_setprio 0
	s_add_i32 s93, s93, 2
	s_add_u32 s36, s36, 0x100
	s_addc_u32 s37, s37, 0
	s_add_u32 s91, s91, 0x100
	s_addc_u32 s92, s92, 0
	s_cmp_gt_u32 s93, 13
	s_barrier
	s_cbranch_scc0 .LBB0_170
	v_lshl_add_u32 v140, s89, 10, v148
	ds_read2_b32 v[154:155], v140 offset1:16
	ds_read2_b32 v[156:157], v140 offset0:32 offset1:48
	ds_read2_b32 v[144:145], v140 offset0:128 offset1:144
	ds_read2_b32 v[142:143], v140 offset0:160 offset1:176
	v_lshl_add_u32 v152, s88, 8, v146
	s_waitcnt lgkmcnt(0)
	v_pk_mul_f32 v[122:123], v[122:123], v[154:155] op_sel_hi:[1,0]
	v_lshl_or_b32 v140, s87, 8, v149
	v_ashrrev_i32_e32 v153, 31, v152
	v_pk_mul_f32 v[126:127], v[126:127], v[154:155] op_sel_hi:[1,0]
	v_pk_mul_f32 v[124:125], v[124:125], v[154:155] op_sel_hi:[1,0]
	v_max_f32_e32 v122, 0, v122
	v_ashrrev_i32_e32 v141, 31, v140
	v_lshlrev_b64 v[162:163], 13, v[152:153]
	v_pk_mul_f32 v[128:129], v[128:129], v[154:155] op_sel_hi:[1,0]
	v_mul_f32_e32 v151, v122, v122
	v_max_f32_e32 v122, 0, v127
	v_max_f32_e32 v123, 0, v123
	v_max_f32_e32 v124, 0, v124
	v_lshl_add_u64 v[162:163], s[4:5], 0, v[162:163]
	v_lshlrev_b64 v[168:169], 1, v[140:141]
	v_max_f32_e32 v126, 0, v126
	v_mul_f32_e32 v122, v122, v122
	v_mul_f32_e32 v127, v123, v123
	v_max_f32_e32 v123, 0, v128
	v_mul_f32_e32 v128, v124, v124
	v_max_f32_e32 v124, 0, v129
	v_max_f32_e32 v125, 0, v125
	v_pk_mul_f32 v[116:117], v[116:117], v[154:155] op_sel_hi:[1,0]
	v_pk_mul_f32 v[114:115], v[114:115], v[154:155] op_sel_hi:[1,0]
	v_lshl_add_u64 v[140:141], v[162:163], 0, v[168:169]
	v_mul_f32_e32 v126, v126, v126
	v_mul_f32_e32 v123, v123, v123
	v_mul_f32_e32 v124, v124, v124
	v_mul_f32_e32 v125, v125, v125
	v_cvt_pk_bf16_f32 v122, v126, v122
	v_pk_mul_f32 v[120:121], v[120:121], v[154:155] op_sel_hi:[1,0]
	v_pk_mul_f32 v[118:119], v[118:119], v[154:155] op_sel_hi:[1,0]
	v_max_f32_e32 v114, 0, v114
	v_max_f32_e32 v115, 0, v115
	v_max_f32_e32 v116, 0, v116
	v_cvt_pk_bf16_f32 v123, v123, v124
	v_cvt_pk_bf16_f32 v124, v151, v127
	v_cvt_pk_bf16_f32 v125, v128, v125
	global_store_dwordx4 v[140:141], v[122:125], off
	v_max_f32_e32 v117, 0, v117
	v_max_f32_e32 v118, 0, v118
	v_mul_f32_e32 v122, v114, v114
	v_max_f32_e32 v114, 0, v119
	v_mul_f32_e32 v119, v115, v115
	v_max_f32_e32 v115, 0, v120
	v_mul_f32_e32 v120, v116, v116
	v_max_f32_e32 v116, 0, v121
	v_mul_f32_e32 v115, v115, v115
	v_mul_f32_e32 v116, v116, v116
	v_mul_f32_e32 v114, v114, v114
	v_mul_f32_e32 v117, v117, v117
	v_cvt_pk_bf16_f32 v115, v115, v116
	v_cvt_pk_bf16_f32 v116, v122, v119
	v_mul_f32_e32 v118, v118, v118
	v_cvt_pk_bf16_f32 v114, v118, v114
	v_cvt_pk_bf16_f32 v117, v120, v117
	global_store_dwordx4 v[140:141], v[114:117], off offset:256
	v_pk_mul_f32 v[90:91], v[90:91], v[156:157] op_sel_hi:[1,0]
	v_pk_mul_f32 v[94:95], v[94:95], v[156:157] op_sel_hi:[1,0]
	v_mov_b32_e32 v116, v155
	v_or_b32_e32 v114, 16, v152
	v_pk_mul_f32 v[106:107], v[106:107], v[116:117] op_sel_hi:[1,0]
	v_ashrrev_i32_e32 v115, 31, v114
	v_pk_mul_f32 v[110:111], v[110:111], v[116:117] op_sel_hi:[1,0]
	v_pk_mul_f32 v[108:109], v[108:109], v[116:117] op_sel_hi:[1,0]
	v_max_f32_e32 v106, 0, v106
; __device__ __forceinline__ unsigned pk2(float lo, float hi) { unsigned r; asm("v_cvt_pk_bf16_f32 %0, %1, %2" : "=v"(r) : "v"(lo), "v"(hi)); return r; }
;     __device__ __forceinline__ void operator()(const f32x4 (&acc)[2][2][4][2], const Unit& u, int ui, int wr, int wc, int fr, int fq) const {
;     ...
;         for (int ai = 0; ai < 2; ++ai)
; #pragma unroll
;             for (int m = 0; m < 4; ++m) {
;                 const int row = row0 + ai * HALF + m * 16; const float rs = rsv[ai][m];
;                 bf16_t* rowp = O + (size_t)row * ldc + col0;
; #pragma unroll
;                 for (int bj = 0; bj < 2; ++bj) {
;                     f32x4 v0 = acc[ai][bj][m][0] * rs, v1 = acc[ai][bj][m][1] * rs;
;                     if (ACT == 1) {
; #pragma unroll
;                         for (int j = 0; j < 4; ++j) { const float a = fmaxf(v0[j], 0.f), b = fmaxf(v1[j], 0.f); v0[j] = a * a; v1[j] = b * b; }
;                     }
;                     u32x4 w; w.x = pk2(v0[0], v0[1]); w.y = pk2(v0[2], v0[3]); w.z = pk2(v1[0], v1[1]); w.w = pk2(v1[2], v1[3]);
;                     *(u32x4*)(rowp + bj * HALF) = w;
;                 }
	v_lshlrev_b64 v[114:115], 13, v[114:115]
	v_pk_mul_f32 v[112:113], v[112:113], v[116:117] op_sel_hi:[1,0]
	v_mul_f32_e32 v117, v106, v106
	v_max_f32_e32 v106, 0, v111
	v_max_f32_e32 v107, 0, v107
	v_max_f32_e32 v108, 0, v108
	v_lshl_add_u64 v[114:115], s[4:5], 0, v[114:115]
	v_max_f32_e32 v110, 0, v110
	v_mul_f32_e32 v106, v106, v106
	v_mul_f32_e32 v111, v107, v107
	v_max_f32_e32 v107, 0, v112
	v_mul_f32_e32 v112, v108, v108
	v_max_f32_e32 v108, 0, v113
	v_max_f32_e32 v109, 0, v109
	v_pk_mul_f32 v[98:99], v[98:99], v[116:117] op_sel_hi:[1,0]
	v_lshl_add_u64 v[114:115], v[114:115], 0, v[168:169]
	v_mul_f32_e32 v110, v110, v110
	v_mul_f32_e32 v107, v107, v107
	v_mul_f32_e32 v108, v108, v108
	v_mul_f32_e32 v109, v109, v109
	v_cvt_pk_bf16_f32 v106, v110, v106
	v_pk_mul_f32 v[102:103], v[102:103], v[116:117] op_sel_hi:[1,0]
	v_pk_mul_f32 v[100:101], v[100:101], v[116:117] op_sel_hi:[1,0]
	v_max_f32_e32 v98, 0, v98
	v_cvt_pk_bf16_f32 v107, v107, v108
	v_cvt_pk_bf16_f32 v108, v117, v111
	v_cvt_pk_bf16_f32 v109, v112, v109
	global_store_dwordx4 v[114:115], v[106:109], off
	v_pk_mul_f32 v[104:105], v[104:105], v[116:117] op_sel_hi:[1,0]
	v_max_f32_e32 v99, 0, v99
	v_mul_f32_e32 v106, v98, v98
	v_max_f32_e32 v98, 0, v103
	v_max_f32_e32 v100, 0, v100
	v_max_f32_e32 v102, 0, v102
	v_mul_f32_e32 v98, v98, v98
	v_mul_f32_e32 v103, v99, v99
	v_max_f32_e32 v99, 0, v104
	v_mul_f32_e32 v104, v100, v100
	v_max_f32_e32 v100, 0, v105
	v_max_f32_e32 v101, 0, v101
	v_mul_f32_e32 v102, v102, v102
	v_mul_f32_e32 v99, v99, v99
	v_mul_f32_e32 v100, v100, v100
	v_mul_f32_e32 v101, v101, v101
	v_cvt_pk_bf16_f32 v98, v102, v98
	v_cvt_pk_bf16_f32 v99, v99, v100
	v_cvt_pk_bf16_f32 v100, v106, v103
	v_cvt_pk_bf16_f32 v101, v104, v101
	global_store_dwordx4 v[114:115], v[98:101], off offset:256
	v_pk_mul_f32 v[92:93], v[92:93], v[156:157] op_sel_hi:[1,0]
	v_max_f32_e32 v90, 0, v90
	v_or_b32_e32 v98, 32, v152
	v_ashrrev_i32_e32 v99, 31, v98
	v_lshlrev_b64 v[98:99], 13, v[98:99]
	v_pk_mul_f32 v[96:97], v[96:97], v[156:157] op_sel_hi:[1,0]
	v_mul_f32_e32 v100, v90, v90
	v_max_f32_e32 v90, 0, v95
	v_max_f32_e32 v91, 0, v91
	v_max_f32_e32 v92, 0, v92
	v_lshl_add_u64 v[98:99], s[4:5], 0, v[98:99]
	v_max_f32_e32 v94, 0, v94
	v_mul_f32_e32 v90, v90, v90
	v_mul_f32_e32 v95, v91, v91
	v_max_f32_e32 v91, 0, v96
	v_mul_f32_e32 v96, v92, v92
	v_max_f32_e32 v92, 0, v97
	v_max_f32_e32 v93, 0, v93
	v_pk_mul_f32 v[84:85], v[84:85], v[156:157] op_sel_hi:[1,0]
	v_pk_mul_f32 v[82:83], v[82:83], v[156:157] op_sel_hi:[1,0]
	v_lshl_add_u64 v[98:99], v[98:99], 0, v[168:169]
	v_mul_f32_e32 v94, v94, v94
	v_mul_f32_e32 v91, v91, v91
	v_mul_f32_e32 v92, v92, v92
	v_mul_f32_e32 v93, v93, v93
	v_cvt_pk_bf16_f32 v90, v94, v90
	v_pk_mul_f32 v[88:89], v[88:89], v[156:157] op_sel_hi:[1,0]
	v_pk_mul_f32 v[86:87], v[86:87], v[156:157] op_sel_hi:[1,0]
	v_max_f32_e32 v82, 0, v82
	v_max_f32_e32 v83, 0, v83
	v_max_f32_e32 v84, 0, v84
	v_cvt_pk_bf16_f32 v91, v91, v92
	v_cvt_pk_bf16_f32 v92, v100, v95
	v_cvt_pk_bf16_f32 v93, v96, v93
	global_store_dwordx4 v[98:99], v[90:93], off
	v_max_f32_e32 v85, 0, v85
	v_max_f32_e32 v86, 0, v86
	v_mul_f32_e32 v90, v82, v82
	v_max_f32_e32 v82, 0, v87
	v_mul_f32_e32 v87, v83, v83
	v_max_f32_e32 v83, 0, v88
	v_mul_f32_e32 v88, v84, v84
	v_max_f32_e32 v84, 0, v89
	v_mul_f32_e32 v83, v83, v83
	v_mul_f32_e32 v84, v84, v84
	v_mul_f32_e32 v82, v82, v82
	v_mul_f32_e32 v85, v85, v85
	v_cvt_pk_bf16_f32 v83, v83, v84
	v_cvt_pk_bf16_f32 v84, v90, v87
	v_mul_f32_e32 v86, v86, v86
	v_cvt_pk_bf16_f32 v82, v86, v82
	v_cvt_pk_bf16_f32 v85, v88, v85
	global_store_dwordx4 v[98:99], v[82:85], off offset:256
	v_pk_mul_f32 v[58:59], v[58:59], v[144:145] op_sel_hi:[1,0]
	v_pk_mul_f32 v[62:63], v[62:63], v[144:145] op_sel_hi:[1,0]
	v_mov_b32_e32 v84, v157
	v_or_b32_e32 v82, 48, v152
	v_pk_mul_f32 v[74:75], v[74:75], v[84:85] op_sel_hi:[1,0]
	v_ashrrev_i32_e32 v83, 31, v82
	v_pk_mul_f32 v[78:79], v[78:79], v[84:85] op_sel_hi:[1,0]
	v_pk_mul_f32 v[76:77], v[76:77], v[84:85] op_sel_hi:[1,0]
	v_max_f32_e32 v74, 0, v74
	v_lshlrev_b64 v[82:83], 13, v[82:83]
	v_pk_mul_f32 v[80:81], v[80:81], v[84:85] op_sel_hi:[1,0]
	v_mul_f32_e32 v85, v74, v74
	v_max_f32_e32 v74, 0, v79
	v_max_f32_e32 v75, 0, v75
	v_max_f32_e32 v76, 0, v76
	v_lshl_add_u64 v[82:83], s[4:5], 0, v[82:83]
	v_max_f32_e32 v78, 0, v78
	v_mul_f32_e32 v74, v74, v74
	v_mul_f32_e32 v79, v75, v75
	v_max_f32_e32 v75, 0, v80
	v_mul_f32_e32 v80, v76, v76
	v_max_f32_e32 v76, 0, v81
	v_max_f32_e32 v77, 0, v77
	v_pk_mul_f32 v[68:69], v[68:69], v[84:85] op_sel_hi:[1,0]
	v_pk_mul_f32 v[66:67], v[66:67], v[84:85] op_sel_hi:[1,0]
	v_lshl_add_u64 v[82:83], v[82:83], 0, v[168:169]
	v_mul_f32_e32 v78, v78, v78
	v_mul_f32_e32 v75, v75, v75
	v_mul_f32_e32 v76, v76, v76
	v_mul_f32_e32 v77, v77, v77
	v_cvt_pk_bf16_f32 v74, v78, v74
	v_pk_mul_f32 v[72:73], v[72:73], v[84:85] op_sel_hi:[1,0]
	v_pk_mul_f32 v[70:71], v[70:71], v[84:85] op_sel_hi:[1,0]
	v_max_f32_e32 v66, 0, v66
	v_max_f32_e32 v67, 0, v67
	v_max_f32_e32 v68, 0, v68
	v_cvt_pk_bf16_f32 v75, v75, v76
	v_cvt_pk_bf16_f32 v76, v85, v79
	v_cvt_pk_bf16_f32 v77, v80, v77
	global_store_dwordx4 v[82:83], v[74:77], off
	v_max_f32_e32 v69, 0, v69
	v_max_f32_e32 v70, 0, v70
	v_mul_f32_e32 v74, v66, v66
	v_max_f32_e32 v66, 0, v71
	v_mul_f32_e32 v71, v67, v67
	v_max_f32_e32 v67, 0, v72
	v_mul_f32_e32 v72, v68, v68
	v_max_f32_e32 v68, 0, v73
	v_mul_f32_e32 v67, v67, v67
	v_mul_f32_e32 v68, v68, v68
	v_mul_f32_e32 v66, v66, v66
	v_mul_f32_e32 v69, v69, v69
	v_cvt_pk_bf16_f32 v67, v67, v68
	v_cvt_pk_bf16_f32 v68, v74, v71
	v_pk_mul_f32 v[60:61], v[60:61], v[144:145] op_sel_hi:[1,0]
	v_max_f32_e32 v58, 0, v58
; __device__ __forceinline__ unsigned pk2(float lo, float hi) { unsigned r; asm("v_cvt_pk_bf16_f32 %0, %1, %2" : "=v"(r) : "v"(lo), "v"(hi)); return r; }
;     __device__ __forceinline__ void operator()(const f32x4 (&acc)[2][2][4][2], const Unit& u, int ui, int wr, int wc, int fr, int fq) const {
;     ...
;         for (int ai = 0; ai < 2; ++ai)
; #pragma unroll
;             for (int m = 0; m < 4; ++m) {
;                 const int row = row0 + ai * HALF + m * 16; const float rs = rsv[ai][m];
;                 bf16_t* rowp = O + (size_t)row * ldc + col0;
; #pragma unroll
;                 for (int bj = 0; bj < 2; ++bj) {
;                     f32x4 v0 = acc[ai][bj][m][0] * rs, v1 = acc[ai][bj][m][1] * rs;
;                     if (ACT == 1) {
; #pragma unroll
;                         for (int j = 0; j < 4; ++j) { const float a = fmaxf(v0[j], 0.f), b = fmaxf(v1[j], 0.f); v0[j] = a * a; v1[j] = b * b; }
;                     }
;                     u32x4 w; w.x = pk2(v0[0], v0[1]); w.y = pk2(v0[2], v0[3]); w.z = pk2(v1[0], v1[1]); w.w = pk2(v1[2], v1[3]);
;                     *(u32x4*)(rowp + bj * HALF) = w;
;                 }
	v_mul_f32_e32 v70, v70, v70
	v_cvt_pk_bf16_f32 v66, v70, v66
	v_cvt_pk_bf16_f32 v69, v72, v69
	global_store_dwordx4 v[82:83], v[66:69], off offset:256
	s_mov_b64 s[6:7], 0x100000
	v_pk_mul_f32 v[64:65], v[64:65], v[144:145] op_sel_hi:[1,0]
	v_max_f32_e32 v62, 0, v62
	v_mul_f32_e32 v68, v58, v58
	v_max_f32_e32 v58, 0, v63
	v_max_f32_e32 v59, 0, v59
	v_max_f32_e32 v60, 0, v60
	v_lshl_add_u64 v[66:67], v[140:141], 0, s[6:7]
	v_mul_f32_e32 v62, v62, v62
	v_mul_f32_e32 v58, v58, v58
	v_mul_f32_e32 v63, v59, v59
	v_max_f32_e32 v59, 0, v64
	v_mul_f32_e32 v64, v60, v60
	v_max_f32_e32 v60, 0, v65
	s_mov_b32 s6, 0x100000
	v_mul_f32_e32 v59, v59, v59
	v_max_f32_e32 v61, 0, v61
	v_mul_f32_e32 v60, v60, v60
	v_cvt_pk_bf16_f32 v58, v62, v58
	v_add_co_u32_e32 v62, vcc, s6, v140
	v_pk_mul_f32 v[52:53], v[52:53], v[144:145] op_sel_hi:[1,0]
	v_pk_mul_f32 v[50:51], v[50:51], v[144:145] op_sel_hi:[1,0]
	v_mul_f32_e32 v61, v61, v61
	v_cvt_pk_bf16_f32 v59, v59, v60
	v_cvt_pk_bf16_f32 v60, v68, v63
	v_addc_co_u32_e32 v63, vcc, 0, v141, vcc
	v_pk_mul_f32 v[56:57], v[56:57], v[144:145] op_sel_hi:[1,0]
	v_pk_mul_f32 v[54:55], v[54:55], v[144:145] op_sel_hi:[1,0]
	v_max_f32_e32 v50, 0, v50
	v_max_f32_e32 v51, 0, v51
	v_max_f32_e32 v52, 0, v52
	v_cvt_pk_bf16_f32 v61, v64, v61
	global_store_dwordx4 v[62:63], v[58:61], off
	v_max_f32_e32 v53, 0, v53
	v_max_f32_e32 v54, 0, v54
	v_mul_f32_e32 v58, v50, v50
	v_max_f32_e32 v50, 0, v55
	v_mul_f32_e32 v55, v51, v51
	v_max_f32_e32 v51, 0, v56
	v_mul_f32_e32 v56, v52, v52
	v_max_f32_e32 v52, 0, v57
	v_mul_f32_e32 v51, v51, v51
	v_mul_f32_e32 v52, v52, v52
	v_mul_f32_e32 v50, v50, v50
	v_mul_f32_e32 v53, v53, v53
	v_cvt_pk_bf16_f32 v51, v51, v52
	v_cvt_pk_bf16_f32 v52, v58, v55
	v_mul_f32_e32 v54, v54, v54
	v_cvt_pk_bf16_f32 v50, v54, v50
	v_cvt_pk_bf16_f32 v53, v56, v53
	global_store_dwordx4 v[66:67], v[50:53], off offset:256
	s_mov_b64 s[6:7], 0x120000
	v_pk_mul_f32 v[26:27], v[26:27], v[142:143] op_sel_hi:[1,0]
	v_mov_b32_e32 v52, v145
	v_pk_mul_f32 v[42:43], v[42:43], v[52:53] op_sel_hi:[1,0]
	v_pk_mul_f32 v[46:47], v[46:47], v[52:53] op_sel_hi:[1,0]
	v_pk_mul_f32 v[44:45], v[44:45], v[52:53] op_sel_hi:[1,0]
	v_max_f32_e32 v42, 0, v42
	v_pk_mul_f32 v[48:49], v[48:49], v[52:53] op_sel_hi:[1,0]
	v_max_f32_e32 v46, 0, v46
	v_mul_f32_e32 v53, v42, v42
	v_max_f32_e32 v42, 0, v47
	v_max_f32_e32 v43, 0, v43
	v_max_f32_e32 v44, 0, v44
	v_lshl_add_u64 v[50:51], v[140:141], 0, s[6:7]
	v_mul_f32_e32 v46, v46, v46
	v_mul_f32_e32 v42, v42, v42
	v_mul_f32_e32 v47, v43, v43
	v_max_f32_e32 v43, 0, v48
	v_mul_f32_e32 v48, v44, v44
	v_max_f32_e32 v44, 0, v49
	s_mov_b32 s6, 0x120000
	v_mul_f32_e32 v43, v43, v43
	v_max_f32_e32 v45, 0, v45
	v_mul_f32_e32 v44, v44, v44
	v_cvt_pk_bf16_f32 v42, v46, v42
	v_add_co_u32_e32 v46, vcc, s6, v140
	v_pk_mul_f32 v[36:37], v[36:37], v[52:53] op_sel_hi:[1,0]
	v_pk_mul_f32 v[34:35], v[34:35], v[52:53] op_sel_hi:[1,0]
	v_mul_f32_e32 v45, v45, v45
	v_cvt_pk_bf16_f32 v43, v43, v44
	v_cvt_pk_bf16_f32 v44, v53, v47
	v_addc_co_u32_e32 v47, vcc, 0, v141, vcc
	v_pk_mul_f32 v[40:41], v[40:41], v[52:53] op_sel_hi:[1,0]
	v_pk_mul_f32 v[38:39], v[38:39], v[52:53] op_sel_hi:[1,0]
	v_max_f32_e32 v34, 0, v34
	v_max_f32_e32 v35, 0, v35
	v_max_f32_e32 v36, 0, v36
	v_cvt_pk_bf16_f32 v45, v48, v45
	global_store_dwordx4 v[46:47], v[42:45], off
	v_max_f32_e32 v37, 0, v37
	v_max_f32_e32 v38, 0, v38
	v_mul_f32_e32 v42, v34, v34
	v_max_f32_e32 v34, 0, v39
	v_mul_f32_e32 v39, v35, v35
	v_max_f32_e32 v35, 0, v40
	v_mul_f32_e32 v40, v36, v36
	v_max_f32_e32 v36, 0, v41
	v_mul_f32_e32 v35, v35, v35
	v_mul_f32_e32 v36, v36, v36
	v_mul_f32_e32 v34, v34, v34
	v_mul_f32_e32 v37, v37, v37
	v_cvt_pk_bf16_f32 v35, v35, v36
	v_cvt_pk_bf16_f32 v36, v42, v39
	v_pk_mul_f32 v[30:31], v[30:31], v[142:143] op_sel_hi:[1,0]
	v_pk_mul_f32 v[28:29], v[28:29], v[142:143] op_sel_hi:[1,0]
	v_max_f32_e32 v26, 0, v26
	v_mul_f32_e32 v38, v38, v38
	v_cvt_pk_bf16_f32 v34, v38, v34
	v_cvt_pk_bf16_f32 v37, v40, v37
	global_store_dwordx4 v[50:51], v[34:37], off offset:256
; __device__ __forceinline__ unsigned pk2(float lo, float hi) { unsigned r; asm("v_cvt_pk_bf16_f32 %0, %1, %2" : "=v"(r) : "v"(lo), "v"(hi)); return r; }
; #define PG8_WAIT_V(n) asm volatile("s_waitcnt vmcnt(" #n ")" ::: "memory")
; #define PG8_BAR __builtin_amdgcn_s_barrier()
;     __device__ __forceinline__ void operator()(const f32x4 (&acc)[2][2][4][2], const Unit& u, int ui, int wr, int wc, int fr, int fq) const {
;     ...
;             for (int m = 0; m < 4; ++m) {
;                 const int row = row0 + ai * HALF + m * 16; const float rs = rsv[ai][m];
;                 bf16_t* rowp = O + (size_t)row * ldc + col0;
; #pragma unroll
;                 for (int bj = 0; bj < 2; ++bj) {
;                     f32x4 v0 = acc[ai][bj][m][0] * rs, v1 = acc[ai][bj][m][1] * rs;
;                     if (ACT == 1) {
; #pragma unroll
;                         for (int j = 0; j < 4; ++j) { const float a = fmaxf(v0[j], 0.f), b = fmaxf(v1[j], 0.f); v0[j] = a * a; v1[j] = b * b; }
;                     }
;                     u32x4 w; w.x = pk2(v0[0], v0[1]); w.y = pk2(v0[2], v0[3]); w.z = pk2(v1[0], v1[1]); w.w = pk2(v1[2], v1[3]);
;                     *(u32x4*)(rowp + bj * HALF) = w;
;                 }
; template <class Epi>
; __device__ __forceinline__ void gemm_phase(LAS unsigned char* lds, const Gemm g, const StaticOrder& S, const Epi& E) {
;     ...
;         E(acc, cur, ui, wr, wc, fr, fq);
;         if (!has_next) break;
; #pragma unroll
;         for (int a = 0; a < 2; ++a)
; #pragma unroll
;             for (int b = 0; b < 2; ++b)
; #pragma unroll
;                 for (int m = 0; m < 4; ++m)
; #pragma unroll
;                     for (int n = 0; n < 2; ++n) acc[a][b][m][n] = (f32x4){0.f, 0.f, 0.f, 0.f};
;         cur = nxt; cA = nA; cB = nB; ++ui;
;     }
;     PG8_WAIT_V(0);
;     if (wr == 0) PG8_BAR;
;     PG8_BAR;
	s_mov_b64 s[6:7], 0x140000
	v_pk_mul_f32 v[32:33], v[32:33], v[142:143] op_sel_hi:[1,0]
	v_max_f32_e32 v30, 0, v30
	v_mul_f32_e32 v36, v26, v26
	v_max_f32_e32 v26, 0, v31
	v_max_f32_e32 v27, 0, v27
	v_max_f32_e32 v28, 0, v28
	v_lshl_add_u64 v[34:35], v[140:141], 0, s[6:7]
	v_mul_f32_e32 v30, v30, v30
	v_mul_f32_e32 v26, v26, v26
	v_mul_f32_e32 v31, v27, v27
	v_max_f32_e32 v27, 0, v32
	v_mul_f32_e32 v32, v28, v28
	v_max_f32_e32 v28, 0, v33
	s_mov_b32 s6, 0x140000
	v_mul_f32_e32 v27, v27, v27
	v_max_f32_e32 v29, 0, v29
	v_mul_f32_e32 v28, v28, v28
	v_cvt_pk_bf16_f32 v26, v30, v26
	v_add_co_u32_e32 v30, vcc, s6, v140
	v_pk_mul_f32 v[20:21], v[20:21], v[142:143] op_sel_hi:[1,0]
	v_pk_mul_f32 v[18:19], v[18:19], v[142:143] op_sel_hi:[1,0]
	v_mul_f32_e32 v29, v29, v29
	v_cvt_pk_bf16_f32 v27, v27, v28
	v_cvt_pk_bf16_f32 v28, v36, v31
	v_addc_co_u32_e32 v31, vcc, 0, v141, vcc
	v_pk_mul_f32 v[24:25], v[24:25], v[142:143] op_sel_hi:[1,0]
	v_pk_mul_f32 v[22:23], v[22:23], v[142:143] op_sel_hi:[1,0]
	v_max_f32_e32 v18, 0, v18
	v_max_f32_e32 v19, 0, v19
	v_max_f32_e32 v20, 0, v20
	v_cvt_pk_bf16_f32 v29, v32, v29
	global_store_dwordx4 v[30:31], v[26:29], off
	v_max_f32_e32 v21, 0, v21
	v_max_f32_e32 v22, 0, v22
	v_mul_f32_e32 v26, v18, v18
	v_max_f32_e32 v18, 0, v23
	v_mul_f32_e32 v23, v19, v19
	v_max_f32_e32 v19, 0, v24
	v_mul_f32_e32 v24, v20, v20
	v_max_f32_e32 v20, 0, v25
	v_mul_f32_e32 v19, v19, v19
	v_mul_f32_e32 v20, v20, v20
	v_mul_f32_e32 v18, v18, v18
	v_mul_f32_e32 v21, v21, v21
	v_cvt_pk_bf16_f32 v19, v19, v20
	v_cvt_pk_bf16_f32 v20, v26, v23
	v_mul_f32_e32 v22, v22, v22
	v_cvt_pk_bf16_f32 v18, v22, v18
	v_cvt_pk_bf16_f32 v21, v24, v21
	global_store_dwordx4 v[34:35], v[18:21], off offset:256
	s_mov_b64 s[6:7], 0x160000
	s_mov_b32 s87, s8
	v_mov_b32_e32 v20, v143
	v_pk_mul_f32 v[10:11], v[10:11], v[20:21] op_sel_hi:[1,0]
	v_pk_mul_f32 v[14:15], v[14:15], v[20:21] op_sel_hi:[1,0]
	v_pk_mul_f32 v[12:13], v[12:13], v[20:21] op_sel_hi:[1,0]
	v_max_f32_e32 v10, 0, v10
	v_pk_mul_f32 v[16:17], v[16:17], v[20:21] op_sel_hi:[1,0]
	v_max_f32_e32 v14, 0, v14
	v_mul_f32_e32 v21, v10, v10
	v_max_f32_e32 v10, 0, v15
	v_max_f32_e32 v11, 0, v11
	v_max_f32_e32 v12, 0, v12
	v_lshl_add_u64 v[18:19], v[140:141], 0, s[6:7]
	v_mul_f32_e32 v14, v14, v14
	v_mul_f32_e32 v10, v10, v10
	v_mul_f32_e32 v15, v11, v11
	v_max_f32_e32 v11, 0, v16
	v_mul_f32_e32 v16, v12, v12
	v_max_f32_e32 v12, 0, v17
	s_mov_b32 s6, 0x160000
	v_mul_f32_e32 v11, v11, v11
	v_max_f32_e32 v13, 0, v13
	v_mul_f32_e32 v12, v12, v12
	v_cvt_pk_bf16_f32 v10, v14, v10
	v_add_co_u32_e32 v14, vcc, s6, v140
	v_pk_mul_f32 v[4:5], v[4:5], v[20:21] op_sel_hi:[1,0]
	v_pk_mul_f32 v[2:3], v[2:3], v[20:21] op_sel_hi:[1,0]
	v_mul_f32_e32 v13, v13, v13
	v_cvt_pk_bf16_f32 v11, v11, v12
	v_cvt_pk_bf16_f32 v12, v21, v15
	v_addc_co_u32_e32 v15, vcc, 0, v141, vcc
	v_pk_mul_f32 v[8:9], v[8:9], v[20:21] op_sel_hi:[1,0]
	v_pk_mul_f32 v[6:7], v[6:7], v[20:21] op_sel_hi:[1,0]
	v_max_f32_e32 v2, 0, v2
	v_max_f32_e32 v3, 0, v3
	v_max_f32_e32 v4, 0, v4
	v_cvt_pk_bf16_f32 v13, v16, v13
	global_store_dwordx4 v[14:15], v[10:13], off
	v_max_f32_e32 v5, 0, v5
	v_max_f32_e32 v6, 0, v6
	v_mul_f32_e32 v10, v2, v2
	v_max_f32_e32 v2, 0, v7
	v_mul_f32_e32 v7, v3, v3
	v_max_f32_e32 v3, 0, v8
	v_mul_f32_e32 v8, v4, v4
	v_max_f32_e32 v4, 0, v9
	v_mul_f32_e32 v2, v2, v2
	v_mul_f32_e32 v3, v3, v3
	v_mul_f32_e32 v4, v4, v4
	v_mul_f32_e32 v5, v5, v5
	s_and_b64 vcc, exec, s[40:41]
	s_mov_b32 s88, s10
	s_mov_b64 s[6:7], s[24:25]
	s_mov_b64 s[36:37], s[12:13]
	s_mov_b32 s89, s86
	v_mul_f32_e32 v6, v6, v6
	v_cvt_pk_bf16_f32 v2, v6, v2
	v_cvt_pk_bf16_f32 v3, v3, v4
	v_cvt_pk_bf16_f32 v4, v10, v7
	v_cvt_pk_bf16_f32 v5, v8, v5
	global_store_dwordx4 v[18:19], v[2:5], off offset:256
	s_cbranch_vccz .LBB0_163
	s_waitcnt vmcnt(0)
	v_readlane_b32 s70, v254, 40
	v_readlane_b32 s84, v254, 42
	s_cmpk_gt_u32 s18, 0xff
	v_readlane_b32 s71, v254, 41
	v_readlane_b32 s86, v254, 44
	v_readlane_b32 s87, v254, 45
	v_readlane_b32 s85, v254, 43
	s_cbranch_scc1 .LBB0_174
	s_barrier
